# final rmsnorm: the 8 loop-invariant gain vectors loaded once before the row loop instead of 8 serialized loads per row
# baseline (speedup 1.0000x reference)
; DI void phase_final(const P& p) {
;     ...
;   const int lane = tid_ & 63, gw = bid_ * 8 + (tid_ >> 6), nw = gridDim.x * 8;
;   const float* x = (const float*)(p.ws + OFF_X);
;   for (int row = gw; row < S_; row += nw) {
;     const float* src = x + (long)row * DM; float4 v[8]; float ss = 0.f;
; #pragma unroll
;     for (int i = 0; i < 8; ++i) { v[i] = *reinterpret_cast<const float4*>(src + i * 256 + lane * 4); ss += v[i].x * v[i].x + v[i].y * v[i].y + v[i].z * v[i].z + v[i].w * v[i].w; }
;     ss = wave_sum(ss);
;     float rr = rsqrtf(ss * (1.f / 2048.f) + EPS);
; #pragma unroll
;     for (int i = 0; i < 8; ++i) {
;       float4 gg = *reinterpret_cast<const float4*>(p.final_norm + i * 256 + lane * 4);
;       float4 o = make_float4(v[i].x * rr * gg.x, v[i].y * rr * gg.y, v[i].z * rr * gg.z, v[i].w * rr * gg.w);
;       *reinterpret_cast<float4*>(p.out + (long)row * DM + i * 256 + lane * 4) = o;
.LBB0_8:
	s_mov_b32 s2, s16
	s_mov_b64 s[4:5], -1
	s_mov_b64 s[0:1], 0
	v_writelane_b32 v254, s2, 60
	s_cmp_lt_i32 s16, 45
	s_mov_b64 s[2:3], 0
	s_cbranch_scc1 .LBB0_30
	v_readlane_b32 s2, v254, 60
	s_cmp_eq_u32 s2, 45
	s_mov_b64 s[2:3], -1
	s_cbranch_scc0 .LBB0_14
	s_waitcnt vmcnt(0)
	v_mov_b32_e32 v3, v204
	s_mov_b32 s2, s77
	s_lshl_b32 s2, s2, 3
	v_ashrrev_i32_e32 v2, 6, v3
	v_add_u32_e32 v46, s2, v2
	v_cmp_gt_i32_e32 vcc, s39, v46
	s_and_saveexec_b64 s[4:5], vcc
	s_cbranch_execz .LBB0_13
	v_lshlrev_b32_e32 v0, 4, v3
	v_readlane_b32 s8, v252, 6
	v_and_b32_e32 v0, 0x3f0, v0
	v_readlane_b32 s9, v252, 7
	s_load_dword s3, s[30:31], 0x0
	v_readlane_b32 s6, v252, 0
	v_lshl_add_u64 v[30:31], s[8:9], 0, v[0:1]
	v_readlane_b32 s8, v252, 2
	v_readlane_b32 s9, v252, 3
	v_readlane_b32 s7, v252, 1
	v_readlane_b32 s10, v252, 8
	v_lshl_add_u64 v[34:35], s[8:9], 0, v[0:1]
	v_readlane_b32 s8, v252, 4
	v_readlane_b32 s9, v252, 5
	v_lshl_add_u64 v[32:33], s[6:7], 0, v[0:1]
	s_waitcnt lgkmcnt(0)
	s_lshl_b32 s6, s3, 3
	v_lshl_add_u64 v[36:37], s[8:9], 0, v[0:1]
	v_readlane_b32 s8, v252, 10
	v_readlane_b32 s9, v252, 11
	s_ashr_i32 s3, s2, 31
	v_readlane_b32 s11, v252, 9
	v_lshl_add_u64 v[38:39], s[8:9], 0, v[0:1]
	v_and_b32_e32 v0, 63, v3
	v_ashrrev_i32_e32 v3, 31, v2
	v_lshl_add_u64 v[2:3], v[2:3], 0, s[2:3]
	v_lshlrev_b64 v[2:3], 13, v[2:3]
	s_ashr_i32 s7, s6, 31
	v_lshlrev_b32_e32 v0, 4, v0
	v_lshl_add_u64 v[40:41], s[46:47], 0, v[2:3]
	s_lshl_b64 s[8:9], s[6:7], 13
	v_lshl_add_u64 v[42:43], s[10:11], 0, v[2:3]
	s_mov_b64 s[10:11], 0
	global_load_dwordx4 v[90:93], v[30:31], off
	global_load_dwordx4 v[94:97], v[30:31], off offset:1024
	global_load_dwordx4 v[98:101], v[30:31], off offset:2048
	global_load_dwordx4 v[102:105], v[30:31], off offset:3072
	global_load_dwordx4 v[106:109], v[32:33], off
	global_load_dwordx4 v[110:113], v[34:35], off
	global_load_dwordx4 v[114:117], v[36:37], off
	global_load_dwordx4 v[118:121], v[38:39], off
	s_waitcnt vmcnt(0)
; DI void phase_final(const P& p) {
;     ...
;   for (int row = gw; row < S_; row += nw) {
;     const float* src = x + (long)row * DM; float4 v[8]; float ss = 0.f;
; #pragma unroll
;     for (int i = 0; i < 8; ++i) { v[i] = *reinterpret_cast<const float4*>(src + i * 256 + lane * 4); ss += v[i].x * v[i].x + v[i].y * v[i].y + v[i].z * v[i].z + v[i].w * v[i].w; }
;     ss = wave_sum(ss);
;     float rr = rsqrtf(ss * (1.f / 2048.f) + EPS);
; #pragma unroll
;     for (int i = 0; i < 8; ++i) {
;       float4 gg = *reinterpret_cast<const float4*>(p.final_norm + i * 256 + lane * 4);
;       float4 o = make_float4(v[i].x * rr * gg.x, v[i].y * rr * gg.y, v[i].z * rr * gg.z, v[i].w * rr * gg.w);
;       *reinterpret_cast<float4*>(p.out + (long)row * DM + i * 256 + lane * 4) = o;
;     }
.LBB0_12:
	v_lshl_add_u64 v[2:3], v[40:41], 0, v[0:1]
	global_load_dwordx4 v[48:51], v[2:3], off
	global_load_dwordx4 v[26:29], v[2:3], off offset:1024
	global_load_dwordx4 v[22:25], v[2:3], off offset:2048
	global_load_dwordx4 v[18:21], v[2:3], off offset:3072
	v_add_co_u32_e32 v2, vcc, s78, v2
	v_mov_b32_e32 v47, v208
	s_nop 0
	v_addc_co_u32_e32 v3, vcc, 0, v3, vcc
	global_load_dwordx4 v[14:17], v[2:3], off
	global_load_dwordx4 v[6:9], v[2:3], off offset:1024
	global_load_dwordx4 v[10:13], v[2:3], off offset:2048
	s_nop 0
	global_load_dwordx4 v[2:5], v[2:3], off offset:3072
	v_mov_b32_e32 v56, v208
	v_mov_b32_e32 v57, v208
	v_mov_b32_e32 v58, v208
	v_mov_b32_e32 v59, v208
	v_mov_b32_e32 v60, v208
	v_lshlrev_b32_e32 v56, 2, v56
	v_lshlrev_b32_e32 v57, 2, v57
	v_lshlrev_b32_e32 v60, 2, v60
	v_lshlrev_b32_e32 v58, 2, v58
	v_lshlrev_b32_e32 v59, 2, v59
	v_xor_b32_e32 v80, 64, v56
	v_xor_b32_e32 v81, 32, v57
	v_xor_b32_e32 v84, 4, v60
	v_xor_b32_e32 v82, 16, v58
	v_xor_b32_e32 v83, 8, v59
	v_lshlrev_b32_e32 v47, 2, v47
	v_xor_b32_e32 v47, 0x80, v47
	v_lshl_add_u64 v[44:45], v[42:43], 0, v[0:1]
	v_add_u32_e32 v46, s6, v46
	v_lshl_add_u64 v[40:41], v[40:41], 0, s[8:9]
	v_lshl_add_u64 v[42:43], v[42:43], 0, s[8:9]
	s_waitcnt vmcnt(7)
	v_pk_mul_f32 v[56:57], v[48:49], v[48:49]
	s_waitcnt vmcnt(6)
	v_pk_mul_f32 v[60:61], v[26:27], v[26:27]
	v_pk_mul_f32 v[58:59], v[50:51], v[50:51]
	v_pk_mul_f32 v[62:63], v[28:29], v[28:29]
	s_waitcnt vmcnt(5)
	v_pk_mul_f32 v[64:65], v[22:23], v[22:23]
	v_add_f32_e32 v85, v60, v61
	v_add_f32_e32 v86, v56, v57
	v_pk_mul_f32 v[66:67], v[24:25], v[24:25]
	s_waitcnt vmcnt(4)
	v_pk_mul_f32 v[68:69], v[18:19], v[18:19]
	v_add_f32_e32 v87, v64, v65
	s_waitcnt vmcnt(3)
	v_mov_b32_e32 v60, v15
	s_waitcnt vmcnt(2)
	v_mov_b32_e32 v61, v7
	v_add_f32_e32 v62, v85, v62
	v_add_f32_e32 v58, v86, v58
	v_pk_mul_f32 v[70:71], v[20:21], v[20:21]
	v_add_f32_e32 v88, v68, v69
	v_mov_b32_e32 v56, v14
	v_mov_b32_e32 v57, v6
	v_add_f32_e32 v66, v87, v66
	v_pk_mul_f32 v[60:61], v[60:61], v[60:61]
	v_add_f32_e32 v62, v62, v63
	v_add_f32_e32 v63, v58, v59
	v_mov_b32_e32 v64, v16
	v_mov_b32_e32 v65, v8
	s_waitcnt vmcnt(1)
	v_mov_b32_e32 v74, v11
	s_waitcnt vmcnt(0)
	v_mov_b32_e32 v75, v3
	v_add_f32_e32 v70, v88, v70
	v_add_f32_e32 v66, v66, v67
	v_pk_fma_f32 v[56:57], v[56:57], v[56:57], v[60:61]
	v_add_f32_e32 v60, v63, v62
	v_mov_b32_e32 v68, v17
	v_mov_b32_e32 v69, v9
	v_mov_b32_e32 v72, v10
	v_mov_b32_e32 v73, v2
	v_pk_mul_f32 v[74:75], v[74:75], v[74:75]
	v_add_f32_e32 v67, v70, v71
	v_pk_fma_f32 v[56:57], v[64:65], v[64:65], v[56:57]
	v_add_f32_e32 v60, v60, v66
	v_mov_b32_e32 v76, v12
	v_mov_b32_e32 v77, v4
	v_pk_fma_f32 v[58:59], v[72:73], v[72:73], v[74:75]
	v_pk_fma_f32 v[56:57], v[68:69], v[68:69], v[56:57]
	v_add_f32_e32 v60, v60, v67
	v_mov_b32_e32 v78, v13
	v_mov_b32_e32 v79, v5
	v_pk_fma_f32 v[58:59], v[76:77], v[76:77], v[58:59]
	v_add_f32_e32 v56, v60, v56
	v_pk_fma_f32 v[58:59], v[78:79], v[78:79], v[58:59]
	v_add_f32_e32 v56, v56, v57
	v_add_f32_e32 v56, v56, v58
	v_add_f32_e32 v56, v56, v59
	ds_bpermute_b32 v47, v47, v56
	s_waitcnt lgkmcnt(0)
	v_add_f32_e32 v47, v56, v47
	ds_bpermute_b32 v56, v80, v47
	s_waitcnt lgkmcnt(0)
	v_add_f32_e32 v47, v47, v56
	ds_bpermute_b32 v56, v81, v47
	s_waitcnt lgkmcnt(0)
	v_add_f32_e32 v47, v47, v56
	ds_bpermute_b32 v56, v82, v47
	s_waitcnt lgkmcnt(0)
	v_add_f32_e32 v47, v47, v56
	ds_bpermute_b32 v56, v83, v47
	s_waitcnt lgkmcnt(0)
	v_add_f32_e32 v47, v47, v56
	ds_bpermute_b32 v56, v84, v47
	s_waitcnt lgkmcnt(0)
	v_add_f32_e32 v47, v47, v56
	v_fmamk_f32 v47, v47, 0x3a000000, v205
	v_mul_f32_e32 v56, 0x4b800000, v47
	v_cmp_gt_f32_e32 vcc, s33, v47
	s_nop 1
	v_cndmask_b32_e32 v47, v47, v56, vcc
	v_rsq_f32_e32 v47, v47
	s_nop 0
	v_mul_f32_e32 v56, 0x45800000, v47
	v_cndmask_b32_e32 v56, v47, v56, vcc
	v_pk_mul_f32 v[48:49], v[48:49], v[56:57] op_sel_hi:[1,0]
	v_pk_mul_f32 v[50:51], v[50:51], v[56:57] op_sel_hi:[1,0]
	s_waitcnt vmcnt(0)
	v_pk_mul_f32 v[48:49], v[90:91], v[48:49]
	v_pk_mul_f32 v[50:51], v[92:93], v[50:51]
	global_store_dwordx4 v[44:45], v[48:51], off
	v_pk_mul_f32 v[26:27], v[26:27], v[56:57] op_sel_hi:[1,0]
	v_pk_mul_f32 v[28:29], v[28:29], v[56:57] op_sel_hi:[1,0]
	v_pk_mul_f32 v[22:23], v[22:23], v[56:57] op_sel_hi:[1,0]
	v_pk_mul_f32 v[24:25], v[24:25], v[56:57] op_sel_hi:[1,0]
	v_pk_mul_f32 v[18:19], v[18:19], v[56:57] op_sel_hi:[1,0]
	v_pk_mul_f32 v[20:21], v[20:21], v[56:57] op_sel_hi:[1,0]
	v_pk_mul_f32 v[14:15], v[14:15], v[56:57] op_sel_hi:[1,0]
	v_pk_mul_f32 v[16:17], v[16:17], v[56:57] op_sel_hi:[1,0]
	v_pk_mul_f32 v[6:7], v[6:7], v[56:57] op_sel_hi:[1,0]
	v_pk_mul_f32 v[8:9], v[8:9], v[56:57] op_sel_hi:[1,0]
	v_pk_mul_f32 v[10:11], v[10:11], v[56:57] op_sel_hi:[1,0]
	v_pk_mul_f32 v[12:13], v[12:13], v[56:57] op_sel_hi:[1,0]
	v_pk_mul_f32 v[2:3], v[2:3], v[56:57] op_sel_hi:[1,0]
	v_pk_mul_f32 v[4:5], v[4:5], v[56:57] op_sel_hi:[1,0]
	s_waitcnt vmcnt(0)
	v_pk_mul_f32 v[26:27], v[94:95], v[26:27]
	v_pk_mul_f32 v[28:29], v[28:29], v[96:97]
	global_store_dwordx4 v[44:45], v[26:29], off offset:1024
	s_waitcnt vmcnt(0)
	v_pk_mul_f32 v[22:23], v[22:23], v[98:99]
	v_pk_mul_f32 v[24:25], v[24:25], v[100:101]
	global_store_dwordx4 v[44:45], v[22:25], off offset:2048
	s_waitcnt vmcnt(0)
	v_pk_mul_f32 v[18:19], v[18:19], v[102:103]
	v_pk_mul_f32 v[20:21], v[20:21], v[104:105]
	global_store_dwordx4 v[44:45], v[18:21], off offset:3072
	v_add_co_u32_e32 v22, vcc, s78, v44
	s_waitcnt vmcnt(0)
	v_pk_mul_f32 v[14:15], v[14:15], v[106:107]
	v_addc_co_u32_e32 v23, vcc, 0, v45, vcc
	v_pk_mul_f32 v[16:17], v[16:17], v[108:109]
	global_store_dwordx4 v[22:23], v[14:17], off
	v_cmp_lt_i32_e32 vcc, s36, v46
	s_or_b64 s[10:11], vcc, s[10:11]
	s_waitcnt vmcnt(0)
	v_pk_mul_f32 v[6:7], v[6:7], v[110:111]
	v_pk_mul_f32 v[8:9], v[8:9], v[112:113]
	global_store_dwordx4 v[22:23], v[6:9], off offset:1024
	s_waitcnt vmcnt(0)
	s_nop 3
	v_pk_mul_f32 v[6:7], v[10:11], v[114:115]
	v_pk_mul_f32 v[8:9], v[12:13], v[116:117]
	global_store_dwordx4 v[22:23], v[6:9], off offset:2048
	s_waitcnt vmcnt(0)
	v_pk_mul_f32 v[2:3], v[2:3], v[118:119]
	v_pk_mul_f32 v[4:5], v[4:5], v[120:121]
	global_store_dwordx4 v[22:23], v[2:5], off offset:3072
	s_andn2_b64 exec, exec, s[10:11]
	s_cbranch_execnz .LBB0_12
